# stack13: stack10 + one static s_setprio 1 for waves 4-7 at the start of the mixer work-queue phase
# speedup vs baseline: 1.0010x; 1.0010x over previous
.LBB0_644:
	s_or_b64 exec, exec, s[2:3]
	v_readlane_b32 s28, v250, 58
	s_add_u32 s6, s96, 0x1c828800
	v_readlane_b32 s29, v250, 59
	s_addc_u32 s7, s97, 0
	s_lshl_b64 s[2:3], s[28:29], 2
	s_add_u32 s2, s6, s2
	s_addc_u32 s3, s7, s3
	v_writelane_b32 v249, s2, 16
	s_add_u32 s4, s96, 0x14708000
	v_readlane_b32 s30, v250, 52
	v_writelane_b32 v249, s3, 17
	v_writelane_b32 v249, s4, 18
	s_addc_u32 s4, s97, 0
	v_writelane_b32 v249, s4, 19
	s_add_u32 s4, s96, 0x18788000
	s_addc_u32 s5, s97, 0
	v_writelane_b32 v249, s4, 20
	v_readlane_b32 s31, v250, 53
	s_waitcnt lgkmcnt(0)
	v_writelane_b32 v249, s5, 21
	s_add_u32 s4, s96, 0x8200000
	s_addc_u32 s5, s97, 0
	v_writelane_b32 v249, s4, 22
	s_lshl_b32 s86, s28, 1
	s_barrier
	v_readfirstlane_b32 s100, v224
	s_nop 3
	s_lshr_b32 s100, s100, 6
	s_cmp_ge_u32 s100, 4
	s_cbranch_scc0 .Lcprio_skip
	s_setprio 1
.Lcprio_skip:
	s_load_dwordx2 s[2:3], s[30:31], 0xf0
	v_writelane_b32 v249, s5, 23
	s_lshl_b64 s[4:5], s[86:87], 2
	s_add_u32 s4, s6, s4
	s_addc_u32 s5, s7, s5
	v_writelane_b32 v249, s4, 24
	s_lshl_b32 s86, s28, 7
	s_load_dwordx4 s[8:11], s[30:31], 0x20
	v_writelane_b32 v249, s5, 25
	s_lshl_b64 s[4:5], s[86:87], 2
	s_waitcnt lgkmcnt(0)
	s_add_u32 s2, s2, s4
	s_addc_u32 s3, s3, s5
	v_writelane_b32 v249, s2, 26
	s_load_dwordx2 s[6:7], s[30:31], 0xd0
	s_load_dwordx4 s[40:43], s[30:31], 0xc0
	v_writelane_b32 v249, s3, 27
	s_add_u32 s2, s96, 0x11440000
	s_addc_u32 s3, s97, 0
	v_writelane_b32 v249, s2, 28
	s_nop 1
	v_writelane_b32 v249, s3, 29
	s_add_u32 s2, s96, 0x12480000
	v_writelane_b32 v249, s2, 30
	s_addc_u32 s2, s97, 0
	v_writelane_b32 v249, s2, 31
	s_lshl_b32 s2, s28, 12
	s_mov_b32 s3, s87
	v_writelane_b32 v249, s2, 32
	s_nop 1
	v_writelane_b32 v249, s3, 33
	s_add_u32 s2, s96, 0x10400000
	s_addc_u32 s3, s97, 0
	v_writelane_b32 v249, s2, 34
	s_nop 1
	v_writelane_b32 v249, s3, 35
	s_add_u32 s2, s96, 0x14500000
	s_addc_u32 s3, s97, 0
	v_writelane_b32 v249, s2, 36
	s_lshl_b32 s73, s28, 3
	s_nop 0
	v_writelane_b32 v249, s3, 37
	s_lshl_b32 s2, s28, 8
	v_writelane_b32 v249, s2, 38
	s_load_dwordx2 s[2:3], s[30:31], 0x30
	v_writelane_b32 v249, s8, 39
	s_waitcnt lgkmcnt(0)
	s_add_u32 s4, s6, s4
	s_addc_u32 s5, s7, s5
	v_writelane_b32 v249, s9, 40
	v_writelane_b32 v249, s10, 41
	v_writelane_b32 v249, s11, 42
	v_writelane_b32 v249, s2, 43
	s_lshl_b32 s22, s28, 18
	s_lshl_b32 s23, s28, 5
	v_writelane_b32 v249, s3, 44
	v_writelane_b32 v249, s4, 45
	s_load_dwordx2 s[2:3], s[30:31], 0x58
	s_nop 0
	v_writelane_b32 v249, s5, 46
	s_lshl_b32 s4, s28, 19
	s_add_i32 s4, s4, 0x60a0000
	v_writelane_b32 v249, s4, 47
	s_or_b32 s4, s22, 0x6308000
	v_writelane_b32 v249, s4, 48
	s_load_dwordx16 s[4:19], s[30:31], 0x68
	v_writelane_b32 v249, s23, 49
	s_load_dwordx2 s[30:31], s[30:31], 0xa8
	s_add_u32 s78, s96, 0xc300000
	v_writelane_b32 v249, s40, 50
	s_addc_u32 s79, s97, 0
	s_lshl_b32 s86, s28, 9
	v_writelane_b32 v249, s41, 51
	s_lshl_b64 s[36:37], s[86:87], 2
	v_writelane_b32 v249, s42, 52
	s_waitcnt lgkmcnt(0)
	s_add_u32 s30, s30, s36
	v_writelane_b32 v249, s43, 53
	s_addc_u32 s31, s31, s37
	v_writelane_b32 v249, s30, 54
	s_add_u32 s23, s96, 0xe380000
	s_nop 0
	v_writelane_b32 v249, s31, 55
	v_writelane_b32 v249, s23, 56
	s_addc_u32 s23, s97, 0
	s_add_u32 s30, s96, 0x4100000
	v_writelane_b32 v249, s23, 57
	s_addc_u32 s31, s97, 0
	v_writelane_b32 v249, s30, 58
	s_lshl_b32 s23, s28, 2
	s_add_u32 s2, s2, s36
	v_writelane_b32 v249, s31, 59
	v_writelane_b32 v249, s23, 60
	v_writelane_b32 v249, s2, 61
	v_writelane_b32 v249, s36, 62
	s_addc_u32 s2, s3, s37
	s_mov_b32 s23, s87
	v_writelane_b32 v248, s2, 0
	s_lshl_b64 s[2:3], s[22:23], 2
	s_add_u32 s2, s26, s2
	s_addc_u32 s3, s27, s3
	s_add_u32 s2, s2, 0x18ed0000
	v_writelane_b32 v248, s2, 1
	s_addc_u32 s2, s3, 0
	v_writelane_b32 v248, s2, 2
	v_writelane_b32 v249, s37, 63
	v_writelane_b32 v248, s21, 3
	s_branch .LBB0_648
